# P0/P1 weight-conversion split moved to 16384 items (8 per wave, balanced); P1 converter CUs reuse the P0 conversion code
# speedup vs baseline: 1.0109x; 1.0109x over previous
; __device__ __forceinline__ void cvt_range(const Args& a, int lo, int hi, int worker, int nworkers, LAS unsigned* T, int lane) {
;     int it = lo + worker;
;     f32x4 va[8], vb[8], wa[8], wb[8]; float sa[8], sb[8], ta[8], tb[8];
;     CvtItem c0{}, c1{};
;     if (it < hi) { cvt_decode(it, a, c0); cvt_load(c0, lane, va, vb, sa, sb); }
;     if (it + nworkers < hi) { cvt_decode(it + nworkers, a, c1); cvt_load(c1, lane, wa, wb, ta, tb); }
;     const int kq = lane >> 4, nq = lane & 15;
;     LAS unsigned* tw = T + (4 * nq) * 33 + kq;
;     const LAS unsigned* tr = T + (lane >> 3) * 33 + 4 * (lane & 7);
;     while (it < hi) {
;         {   CvtItem cc = c0;
;             cvt_lds_write(tw, va, vb, sa, sb);
;             if (it + 2 * nworkers < hi) { cvt_decode(it + 2 * nworkers, a, c0); cvt_load(c0, lane, va, vb, sa, sb); }
;             cvt_store(tr, cc, lane); }
;         it += nworkers; if (it >= hi) break;
;         {   CvtItem cc = c1;
;             cvt_lds_write(tw, wa, wb, ta, tb);
;             if (it + 2 * nworkers < hi) { cvt_decode(it + 2 * nworkers, a, c1); cvt_load(c1, lane, wa, wb, ta, tb); }
;             cvt_store(tr, cc, lane); }
;         it += nworkers;
;     }
; }
; __device__ __forceinline__ void cvt_decode(int it, const Args& a, CvtItem& c) {
;     unsigned char* ws = a.ws; int q = it;
;     if (q < CI_IN) { const int nblk = INC / 64, kb = q / nblk, nbk = q % nblk; c.src = a.in[2] + (size_t)(64 * kb) * INC + 64 * nbk; c.ldw = INC; c.dst = (bf16_t*)(ws + WS_WIN) + (size_t)(64 * nbk) * DM + 64 * kb; c.ldt = DM; c.ks = nullptr; return; } q -= CI_IN;
;     if (q < CI_PW) { const int per = (PGW / 64) * (PGW / 64), grp = q / per, qq = q % per, nblk = PGW / 64, kb = qq / nblk, nbk = qq % nblk;
;         c.src = a.in[6] + (size_t)grp * PGW * PGW + (size_t)(64 * kb) * PGW + 64 * nbk; c.ldw = PGW; c.dst = (bf16_t*)(ws + WS_PWT) + (size_t)(grp * PGW + 64 * nbk) * PGW + 64 * kb; c.ldt = PGW; c.ks = nullptr; return; } q -= CI_PW;
;     if (q < CI_WO) { const int nblk = DM / 64, kb = q / nblk, nbk = q % nblk; c.src = a.in[8] + (size_t)(64 * kb) * DM + 64 * nbk; c.ldw = DM; c.dst = (bf16_t*)(ws + WS_WO) + (size_t)(64 * nbk) * DM + 64 * kb; c.ldt = DM; c.ks = nullptr; return; } q -= CI_WO;
;     if (q < 2 * CI_G) { const int up = q >= CI_G ? 1 : 0, qq = q - up * CI_G, nblk = DFF / 64, kb = qq / nblk, nbk = qq % nblk, n0 = 64 * nbk;
.LBB0_5:
	s_or_b64 exec, exec, s[0:1]
	s_lshr_b32 s90, s24, 6
	s_lshl_b32 s0, s48, 3
	s_add_i32 s88, s90, s0
	s_cmpk_eq_i32 s62, 0x100
	s_cselect_b64 s[0:1], -1, 0
	s_add_u32 s53, s60, 0x2800000
	s_addc_u32 s80, s61, 0
	s_add_u32 s81, s60, 0x2a00000
	s_addc_u32 s82, s61, 0
	s_add_u32 s83, s60, 0x4a00000
	v_writelane_b32 v243, s24, 24
	s_addc_u32 s84, s61, 0
	v_writelane_b32 v243, s0, 25
	s_cmpk_lg_i32 s62, 0x100
	s_mov_b32 s2, 0xa600
	v_writelane_b32 v243, s1, 26
	s_cselect_b64 s[0:1], -1, 0
	v_writelane_b32 v243, s0, 27
	s_nop 1
	v_writelane_b32 v243, s1, 28
	s_and_b64 s[0:1], s[0:1], exec
	s_cselect_b32 s24, s2, 0x4000
.Lcvt_entry:
	s_cmp_lt_i32 s88, s24
	s_cselect_b64 s[2:3], -1, 0
	s_cmp_ge_i32 s88, s24
	s_cbranch_scc1 .LBB0_12
	s_cmpk_gt_i32 s88, 0x13ff
	s_cbranch_scc0 .LBB0_13
	s_cmpk_gt_u32 s88, 0x14ff
	s_cbranch_scc0 .LBB0_14
	s_cmpk_gt_u32 s88, 0x24ff
	s_cbranch_scc0 .LBB0_15
	s_cmpk_gt_u32 s88, 0x7aff
	s_cbranch_scc0 .LBB0_170
	s_and_b32 s0, s88, 0x7fffffc0
	s_add_i32 s6, s0, 0xffff8500
	s_mov_b32 s7, 0
	s_lshl_b64 s[0:1], s[6:7], 14
	s_add_u32 s0, s56, s0
	s_addc_u32 s1, s57, s1
	s_lshl_b32 s8, s88, 6
	s_and_b32 s8, s8, 0xfc0
	s_lshl_b32 s9, s8, 2
	s_add_u32 s0, s0, s9
	s_addc_u32 s1, s1, 0
	s_mulk_i32 s8, 0x5600
	s_add_u32 s8, s60, s8
	s_addc_u32 s9, s61, 0
	s_lshl_b64 s[6:7], s[6:7], 1
	s_add_u32 s6, s8, s6
	s_addc_u32 s7, s9, s7
	s_add_u32 s10, s6, 0xf600000
	s_addc_u32 s11, s7, 0
	s_mov_b64 s[14:15], 0
	s_cbranch_execz .LBB0_171
	s_mov_b64 s[8:9], 0x1000
	s_movk_i32 s12, 0x2b00
	s_mov_b64 s[6:7], 0
	s_andn2_b64 vcc, exec, s[14:15]
	s_cbranch_vccz .LBB0_16
	s_branch .LBB0_17

; #define LAS __attribute__((address_space(3)))
; __device__ __forceinline__ void cvt_range(const Args& a, int lo, int hi, int worker, int nworkers, LAS unsigned* T, int lane) {
;     int it = lo + worker;
;     f32x4 va[8], vb[8], wa[8], wb[8]; float sa[8], sb[8], ta[8], tb[8];
;     CvtItem c0{}, c1{};
;     if (it < hi) { cvt_decode(it, a, c0); cvt_load(c0, lane, va, vb, sa, sb); }
;     if (it + nworkers < hi) { cvt_decode(it + nworkers, a, c1); cvt_load(c1, lane, wa, wb, ta, tb); }
;     const int kq = lane >> 4, nq = lane & 15;
;     LAS unsigned* tw = T + (4 * nq) * 33 + kq;
;     const LAS unsigned* tr = T + (lane >> 3) * 33 + 4 * (lane & 7);
.LBB0_46:
	s_lshl_b32 s1, s90, 14
	s_mov_b32 s15, 0
	s_add_i32 s85, s1, 0
	s_andn2_b64 vcc, exec, s[2:3]
	v_lshrrev_b32_e32 v213, 4, v212
	s_cbranch_vccnz .LBB0_92
	v_mul_u32_u24_e32 v1, 0x84, v152
	v_lshlrev_b32_e32 v5, 2, v213
	v_and_b32_e32 v3, 28, v3
	s_lshl_b32 s1, s62, 4
	v_add3_u32 v1, s85, v1, v5
	v_mul_i32_i24_e32 v5, 0x84, v148
	v_lshlrev_b32_e32 v3, 2, v3
	s_add_u32 s25, s60, 0xf600000
	v_add3_u32 v149, s85, v5, v3
	v_lshlrev_b32_e32 v3, 3, v195
	s_addc_u32 s26, s61, 0
	s_lshl_b32 s2, s88, 6
	s_mov_b32 s3, 0
	v_mov_b32_e32 v185, 0
	v_and_b32_e32 v184, 56, v3
	s_add_i32 s29, s2, s3
	s_lshl_b32 s2, s88, 3
	s_mov_b32 s3, 0
	v_and_b32_e32 v182, 6, v148
	v_mov_b32_e32 v153, v185
	s_mul_i32 s27, s62, 24
	s_mul_i32 s28, s62, 0x600
	s_lshl_b32 s30, s62, 10
	s_mul_i32 s31, s62, 0xc0
	s_add_i32 s33, s2, s3
	s_lshl_b32 s34, s62, 7
	v_lshlrev_b32_e32 v186, 1, v184
	s_mov_b32 s9, s88
	s_mov_b64 s[2:3], s[10:11]
	s_branch .LBB0_52

; __device__ __forceinline__ unsigned cvtpk(float lo, float hi) { f32x2_t v = {lo, hi}; bf16x2_t b = __builtin_convertvector(v, bf16x2_t); return __builtin_bit_cast(unsigned, b); }
; __global__ void __launch_bounds__(NWAVES * 64, 2) fwd_kernel(Args args) {
;     ...
;         for (int m = gw; m < SEQ; m += NGW) {
;             const f32x4* xr = (const f32x4*)(x + (size_t)m * DM) + lane; const f32x4* gr = (const f32x4*)norm1_g + lane;
;             f32x4 v[16]; float s = 0.f;
; #pragma unroll
;             for (int j = 0; j < 16; ++j) { v[j] = __builtin_nontemporal_load(xr + 64 * j); s += (v[j][0] * v[j][0] + v[j][1] * v[j][1]) + (v[j][2] * v[j][2] + v[j][3] * v[j][3]); }
;             const float rstd = __builtin_amdgcn_rsqf(wave_sum(s) * (1.0f / DM) + EPS);
;             u32x2* o8 = (u32x2*)(XN + (size_t)m * DM) + lane;
; #pragma unroll
;             for (int j = 0; j < 16; ++j) { const f32x4 gg = gr[64 * j]; const f32x4 y = v[j] * rstd * gg; u32x2 w; w.x = cvtpk(y[0], y[1]); w.y = cvtpk(y[2], y[3]); o8[64 * j] = w; }
;         }
.LBB0_92:
	s_cmpk_eq_i32 s24, 0x7b00
	s_cbranch_scc1 .Lcvt_ret_p1
	s_cmpk_gt_i32 s88, 0x1fff
	v_mbcnt_lo_u32_b32 v214, -1, 0
	s_waitcnt vmcnt(3)
	v_lshlrev_b32_e32 v196, 3, v212
	s_cbranch_scc1 .LBB0_95
	v_readlane_b32 s8, v243, 8
	v_lshlrev_b32_e32 v2, 4, v212
	v_mov_b32_e32 v3, 0
	v_readlane_b32 s10, v243, 10
	v_readlane_b32 s11, v243, 11
	s_mov_b64 s[2:3], 0x1000
	v_mbcnt_hi_u32_b32 v4, -1, v214
	v_lshl_add_u64 v[46:47], s[10:11], 0, v[2:3]
	v_lshl_add_u64 v[48:49], v[46:47], 0, s[2:3]
	s_mov_b64 s[2:3], 0x1400
	v_and_b32_e32 v1, 64, v4
	v_lshl_add_u64 v[50:51], v[46:47], 0, s[2:3]
	s_mov_b64 s[2:3], 0x1800
	v_add_u32_e32 v5, 64, v1
	v_xor_b32_e32 v1, 1, v4
	v_lshl_add_u64 v[52:53], v[46:47], 0, s[2:3]
	s_mov_b64 s[2:3], 0x1c00
	v_cmp_lt_i32_e32 vcc, v1, v5
	v_xor_b32_e32 v6, 2, v4
	v_lshl_add_u64 v[54:55], v[46:47], 0, s[2:3]
	s_mov_b64 s[2:3], 0x2000
	v_cndmask_b32_e32 v1, v4, v1, vcc
	v_cmp_lt_i32_e32 vcc, v6, v5
	v_lshl_add_u64 v[56:57], v[46:47], 0, s[2:3]
	s_mov_b64 s[2:3], 0x2400
	v_cndmask_b32_e32 v6, v4, v6, vcc
	v_lshl_add_u64 v[58:59], v[46:47], 0, s[2:3]
	s_mov_b64 s[2:3], 0x2800
	v_lshlrev_b32_e32 v76, 2, v6
	v_xor_b32_e32 v6, 4, v4
	v_lshl_add_u64 v[60:61], v[46:47], 0, s[2:3]
	s_mov_b64 s[2:3], 0x2c00
	v_cmp_lt_i32_e32 vcc, v6, v5
	s_waitcnt vmcnt(0)
	v_lshl_add_u64 v[62:63], v[46:47], 0, s[2:3]
	s_mov_b64 s[2:3], 0x3000
	v_cndmask_b32_e32 v6, v4, v6, vcc
	v_lshl_add_u64 v[64:65], v[46:47], 0, s[2:3]
	s_mov_b64 s[2:3], 0x3400
	v_lshlrev_b32_e32 v77, 2, v6
	v_xor_b32_e32 v6, 8, v4
	v_lshl_add_u64 v[66:67], v[46:47], 0, s[2:3]
	s_mov_b64 s[2:3], 0x3800
	v_cmp_lt_i32_e32 vcc, v6, v5
	v_lshl_add_u64 v[68:69], v[46:47], 0, s[2:3]
	s_mov_b64 s[2:3], 0x3c00
	s_ashr_i32 s89, s88, 31
	v_cndmask_b32_e32 v6, v4, v6, vcc
	v_lshl_add_u64 v[70:71], v[46:47], 0, s[2:3]
	s_lshl_b64 s[2:3], s[88:89], 14
	v_readlane_b32 s9, v243, 9
	v_lshlrev_b32_e32 v78, 2, v6
	v_xor_b32_e32 v6, 16, v4
	s_add_u32 s2, s8, s2
	v_cmp_lt_i32_e32 vcc, v6, v5
	s_addc_u32 s3, s9, s3
	s_ashr_i32 s1, s0, 31
	v_cndmask_b32_e32 v6, v4, v6, vcc
	v_lshl_add_u64 v[72:73], s[2:3], 0, v[2:3]
	s_lshl_b64 s[2:3], s[0:1], 14
	s_lshl_b64 s[6:7], s[88:89], 13
	v_lshlrev_b32_e32 v79, 2, v6
	v_xor_b32_e32 v6, 32, v4
	s_add_u32 s6, s60, s6
	v_cmp_lt_i32_e32 vcc, v6, v5
	v_mov_b32_e32 v197, v3
	s_addc_u32 s7, s61, s7
	v_cndmask_b32_e32 v4, v4, v6, vcc
	v_lshl_add_u64 v[2:3], s[6:7], 0, v[196:197]
	s_mov_b64 s[6:7], 0x14c00000
	v_lshlrev_b32_e32 v1, 2, v1
	v_lshlrev_b32_e32 v80, 2, v4
	v_lshl_add_u64 v[74:75], v[2:3], 0, s[6:7]
	s_lshl_b64 s[6:7], s[0:1], 13
	s_movk_i32 s1, 0x1000
	s_movk_i32 s8, 0x2000
	s_movk_i32 s9, 0x3000
	v_mov_b32_e32 v81, 0x358637bd
	s_mov_b32 s10, s88
	v_readlane_b32 s12, v243, 12
	v_readlane_b32 s13, v243, 13
	v_readlane_b32 s14, v243, 14
	v_readlane_b32 s15, v243, 15
	v_readlane_b32 s16, v243, 16
	v_readlane_b32 s17, v243, 17
	v_readlane_b32 s18, v243, 18
	v_readlane_b32 s19, v243, 19
	v_readlane_b32 s20, v243, 20
	v_readlane_b32 s21, v243, 21
	v_readlane_b32 s22, v243, 22
	v_readlane_b32 s23, v243, 23

; #define LAS __attribute__((address_space(3)))
; __global__ void __launch_bounds__(NWAVES * 64, 2) fwd_kernel(Args args) {
;     ...
;         if (!split_roles || bid < P1_GEMM_CUS) {
;             pg8::Gemm g{XN, WinT, DM, DM, DM, 0, 0}; pg8::StaticOrder S; S.init(SEQ, INC, split_roles ? P1_GEMM_CUS : G, bid);
;             pg8::EpiStore E{QKVP, INC};
;             pg8::gemm_phase<pg8::EpiStore, true>(lds, g, S, E);
;         } else {
;             cvt_range(args, CVT_SPLIT, CI_TOTAL - CI_D, (bid - P1_GEMM_CUS) * NWAVES + wave, (G - P1_GEMM_CUS) * NWAVES, (LAS unsigned*)(lds + wave * 16384), lane);
;         }
.LBB0_159:
	v_writelane_b32 v243, s85, 29
	s_or_b64 exec, exec, s[0:1]
	s_add_u32 s86, s60, 0x14c00000
	s_addc_u32 s87, s61, 0
	s_add_u32 s98, s60, 0x18e00000
	s_addc_u32 s99, s61, 0
	v_readlane_b32 s4, v243, 27
	s_cmpk_gt_i32 s48, 0xd7
	v_readlane_b32 s5, v243, 28
	s_cselect_b64 s[2:3], -1, 0
	s_xor_b64 s[4:5], s[4:5], -1
	s_and_b64 s[2:3], s[2:3], s[4:5]
	s_mov_b64 s[0:1], -1
	s_and_b64 vcc, exec, s[2:3]
	s_waitcnt lgkmcnt(0)
	s_barrier
	s_cbranch_vccz .LBB0_240
	s_addk_i32 s88, 0x3940
	s_movk_i32 s62, 40
	s_movk_i32 s24, 0x7b00
	s_branch .Lcvt_entry
.Lcvt_ret_p1:
	s_lshl_b32 s0, s48, 3
	s_add_i32 s88, s90, s0
	s_movk_i32 s62, 0x100
	v_mbcnt_lo_u32_b32 v214, -1, 0
	v_lshlrev_b32_e32 v196, 3, v212
	s_branch .LBB0_257

; template <class Epi, bool ALIGN_EPI, bool SP2 = PG8_SP2_DEFAULT>
; __device__ __forceinline__ void gemm_phase(LAS unsigned char* lds, const Gemm g, const StaticOrder& S, const Epi& E) {
;     ...
;     const int wid = __builtin_amdgcn_readfirstlane(tid >> 6), lane = tid & 63, wr = wid >> 2, wc = wid & 3, fr = lane & 15, fq = lane >> 4;
;     const int K = g.K, nt = K / BK;
;     unsigned voffA[2], voffB[2];
; #pragma unroll
;     for (int i = 0; i < 2; ++i) { int R, C; stage_rc(tid * 16 + i * 8192, R, C); const int Rb = (R & ~31) + perm32(R & 31);
;         voffA[i] = (unsigned)(R * g.lda + C) * 2u; voffB[i] = (unsigned)(Rb * g.ldb + C) * 2u; }
;     const size_t kstep = (size_t)(BK * 2);
;     const size_t hstepA = (size_t)HALF * g.lda * 2, hstepB = (size_t)HALF * g.ldb * 2;
;     const size_t tstepA = 2 * hstepA, tstepB = 2 * hstepB;
;     const unsigned ldsw = (unsigned)wid * 1024u;
;     const int aoff = lds_byte(wr * 64 + fr, fq * 8), boff = lds_byte(wc * 32 + fr, fq * 8);
;     ...
;     Unit cur, nxt; int ui = 0;
;     if (!S.next(0, cur)) return;
;     f32x4 acc[2][2][4][2];
; #pragma unroll
;     for (int a = 0; a < 2; ++a)
; #pragma unroll
;         for (int b = 0; b < 2; ++b)
; #pragma unroll
;             for (int m = 0; m < 4; ++m)
; #pragma unroll
;                 for (int n = 0; n < 2; ++n) acc[a][b][m][n] = (f32x4){0.f, 0.f, 0.f, 0.f};
;     bf16x8 At[4][2], B0[2][2], B1[2][2];
;     const char* cA = PG8_ABASE(cur); const char* cB = (const char*)g.Bt + (size_t)cur.pn * tstepB;
;     if constexpr (SP2) {
;     PG8_STAGE(PG8_SB(0, 0), cB, voffB); PG8_STAGE(PG8_SB(0, 1), cB + hstepB, voffB); PG8_STAGE(PG8_SA(0, 0), cA, voffA); PG8_STAGE(PG8_SA(0, 1), cA + hstepA, voffA);
;     if (wr == 1) PG8_BAR;
;     PG8_WAIT_V(2); PG8_BAR;
;     PG8_STAGE(PG8_SB(1, 0), cB + kstep, voffB); PG8_STAGE(PG8_SA(1, 0), cA + kstep, voffA); PG8_STAGE(PG8_SB(1, 1), cB + hstepB + kstep, voffB);
; __device__ __forceinline__ void cvt_decode(int it, const Args& a, CvtItem& c) {
;     ...
;     if (q < 2 * CI_G) { const int up = q >= CI_G ? 1 : 0, qq = q - up * CI_G, nblk = DFF / 64, kb = qq / nblk, nbk = qq % nblk, n0 = 64 * nbk;
;         c.src = (up ? a.in[11] : a.in[10]) + (size_t)(64 * kb) * DFF + n0; c.ldw = DFF; c.dst = (bf16_t*)(ws + WS_WGU) + (size_t)((n0 >> 7) * 256 + up * 128 + (n0 & 127)) * DM + 64 * kb; c.ldt = DM; c.ks = a.in[9] + 64 * kb; return; } q -= 2 * CI_G;
.LBB0_173:
	s_cmpk_gt_u32 s1, 0x4fff
	v_readlane_b32 s36, v243, 0
	s_cselect_b32 s6, 0xd500, 0
	v_readlane_b32 s40, v243, 4
	v_readlane_b32 s41, v243, 5
	v_readlane_b32 s42, v243, 6
	v_readlane_b32 s43, v243, 7
	s_cselect_b32 s7, 0x80, 0
	s_cselect_b32 s8, s42, s40
	s_cselect_b32 s9, s43, s41
	s_add_i32 s6, s1, s6
	s_add_i32 s6, s6, 0xdb00
	s_and_b32 s13, s6, 0xffff
	s_mul_i32 s13, s13, 0xbe83
	s_lshr_b32 s13, s13, 23
	s_mul_i32 s14, s13, 0xac
	s_sub_i32 s6, s6, s14
	s_and_b32 s6, s6, 0xffff
	s_lshl_b32 s16, s6, 6
	s_mul_i32 s14, s13, 0x2b0000
	s_add_u32 s8, s8, s14
	s_addc_u32 s9, s9, 0
	s_lshl_b32 s14, s6, 8
	s_add_u32 s14, s8, s14
	s_addc_u32 s15, s9, 0
	s_lshl_b32 s6, s6, 7
	s_and_b32 s6, s6, 0x7f00
	s_or_b32 s6, s7, s6
	s_and_b32 s7, s16, 64
	s_or_b32 s6, s6, s7
	s_lshl_b32 s6, s6, 13
	s_add_u32 s6, s83, s6
	s_addc_u32 s7, s84, 0
	s_lshl_b32 s8, s13, 7
	s_add_u32 s6, s6, s8
	v_readlane_b32 s38, v243, 2
	s_addc_u32 s7, s7, 0
	s_lshl_b32 s8, s13, 8
	v_readlane_b32 s39, v243, 3
	s_add_u32 s16, s38, s8
	v_readlane_b32 s37, v243, 1
	s_addc_u32 s17, s39, 0
	s_mov_b64 s[18:19], 0x2b00
	s_movk_i32 s8, 0x1000
	s_andn2_b64 vcc, exec, s[20:21]
	s_cbranch_vccz .LBB0_38
	s_branch .LBB0_39
.LBB0_240:
	s_and_b64 vcc, exec, s[0:1]
	s_cbranch_vccz .LBB0_257
	v_mov_b32_e32 v10, v195
	s_cmpk_gt_i32 s48, 0x27f
	v_readfirstlane_b32 s1, v10
	s_cbranch_scc1 .LBB0_257
	v_lshlrev_b32_e32 v0, 4, v10
	v_add_u32_e32 v1, 0x2000, v0
	v_ashrrev_i32_e32 v2, 31, v1
	v_lshrrev_b32_e32 v2, 22, v2
	v_add_u32_e32 v2, v1, v2
	v_ashrrev_i32_e32 v8, 10, v2
	v_mul_i32_i24_e32 v2, 0x400, v8
	v_sub_u32_e32 v1, v1, v2
	v_lshrrev_b32_e32 v2, 4, v1
	v_bitop3_b32 v1, v2, v1, 32 bitop3:0x6c
	v_ashrrev_i32_e32 v2, 31, v1
	v_lshrrev_b32_e32 v2, 26, v2
	v_add_u32_e32 v2, v1, v2
	v_lshlrev_b32_e32 v3, 3, v8
	v_ashrrev_i32_e32 v9, 6, v2
	v_and_b32_e32 v3, -16, v3
	v_add_u32_e32 v3, v9, v3
	v_and_b32_e32 v4, 3, v9
	s_mov_b32 s0, 0x7ffe0
	v_lshrrev_b32_e32 v5, 2, v3
	v_lshlrev_b32_e32 v6, 1, v3
	v_and_b32_e32 v2, 0xc0, v2
	v_and_or_b32 v4, v3, s0, v4
	v_and_b32_e32 v5, 4, v5
	v_and_b32_e32 v6, 24, v6
	v_sub_u32_e32 v1, v1, v2
	v_mov_b32_e32 v2, 1
	v_or3_b32 v4, v4, v5, v6
	v_lshlrev_b32_e32 v5, 5, v8
	v_ashrrev_i16_sdwa v1, v2, sext(v1) dst_sel:DWORD dst_unused:UNUSED_PAD src0_sel:DWORD src1_sel:BYTE_0
	v_and_b32_e32 v5, 32, v5
	v_bfe_i32 v11, v1, 0, 16
	v_add_lshl_u32 v1, v5, v11, 1
	s_waitcnt vmcnt(0)
	v_lshl_add_u32 v128, v4, 13, v1
	v_lshl_add_u32 v130, v3, 13, v1
	v_bfe_i32 v1, v10, 27, 1
	v_lshrrev_b32_e32 v1, 22, v1
	v_add_u32_e32 v1, v0, v1
	v_and_b32_e32 v1, 0xfffffc00, v1
	v_sub_u32_e32 v0, v0, v1
	v_lshrrev_b32_e32 v1, 4, v0
	v_ashrrev_i32_e32 v3, 31, v10
	v_bitop3_b32 v0, v1, v0, 32 bitop3:0x6c
	v_lshrrev_b32_e32 v3, 26, v3
	v_ashrrev_i32_e32 v1, 31, v0
	v_add_u32_e32 v3, v10, v3
	v_lshrrev_b32_e32 v1, 26, v1
	v_ashrrev_i32_e32 v13, 6, v3
	v_add_u32_e32 v1, v0, v1
	v_lshlrev_b32_e32 v3, 3, v13
	v_ashrrev_i32_e32 v12, 6, v1
	v_and_b32_e32 v3, -16, v3
	v_add_u32_e32 v3, v12, v3
	v_and_b32_e32 v4, 3, v12
	s_ashr_i32 s25, s48, 31
	v_and_or_b32 v4, v3, s0, v4
	s_lshr_b32 s0, s25, 29
	s_add_i32 s0, s48, s0
	s_ashr_i32 s4, s1, 6
	s_ashr_i32 s2, s0, 3
	s_and_b32 s0, s0, -8
	s_ashr_i32 s6, s1, 8
	s_lshl_b32 s24, s4, 10
	s_sub_i32 s0, s48, s0
	s_cmp_lt_i32 s0, 0
	s_movk_i32 s26, 0x51
	s_cselect_b32 s3, s26, 0x50
	s_mul_i32 s0, s0, s3
	s_add_i32 s0, s0, s2
	s_mul_hi_i32 s2, s0, 0x66666667
	s_lshr_b32 s3, s2, 31
	s_ashr_i32 s2, s2, 6
	s_add_i32 s2, s2, s3
	s_lshl_b32 s3, s2, 3
	s_mulk_i32 s2, 0xa0
	s_sub_i32 s2, s0, s2
	s_sext_i32_i16 s0, s2
	s_bfe_u32 s0, s0, 0x3001c
	s_add_i32 s5, s2, s0
	s_sext_i32_i16 s0, s5
	s_and_b32 s5, s5, 0xfff8
	s_sub_i32 s2, s2, s5
	s_sext_i32_i16 s2, s2
	v_lshrrev_b32_e32 v5, 2, v3
	v_lshlrev_b32_e32 v6, 1, v3
	v_and_b32_e32 v1, 0xc0, v1
	s_lshr_b32 s0, s0, 3
	s_add_i32 s8, s3, s2
	v_and_b32_e32 v5, 4, v5
	v_and_b32_e32 v6, 24, v6
	v_sub_u32_e32 v0, v0, v1
	s_ashr_i32 s9, s8, 31
	s_bfe_i64 s[10:11], s[0:1], 0x100000
	v_or3_b32 v4, v4, v5, v6
	v_lshlrev_b32_e32 v5, 5, v13
	v_ashrrev_i16_sdwa v0, v2, sext(v0) dst_sel:DWORD dst_unused:UNUSED_PAD src0_sel:DWORD src1_sel:BYTE_0
	s_lshl_b64 s[2:3], s[8:9], 21
	s_lshl_b64 s[10:11], s[10:11], 21
	v_and_b32_e32 v5, 32, v5
	v_bfe_i32 v14, v0, 0, 16
	s_add_u32 s20, s60, s10
	v_add_lshl_u32 v0, v5, v14, 1
	s_addc_u32 s21, s61, s11
	s_add_i32 s9, s24, 0
	v_lshl_add_u32 v132, v4, 13, v0
	s_add_i32 m0, s9, 0x10000
	v_lshl_add_u32 v134, v3, 13, v0
	global_load_lds_dwordx4 v132, s[20:21]
	s_add_i32 m0, s9, 0x12000
	s_add_u32 s10, s20, 0x100000
	global_load_lds_dwordx4 v128, s[20:21]
	s_addc_u32 s11, s21, 0
	s_add_i32 m0, s9, 0x14000
	v_mov_b32_e32 v133, 0
	global_load_lds_dwordx4 v132, s[10:11]
	s_add_i32 m0, s9, 0x16000
	s_add_u32 s18, s86, s2
	s_addc_u32 s19, s87, s3
	s_add_i32 s27, s9, 0x2000
	global_load_lds_dwordx4 v128, s[10:11]
	s_mov_b32 m0, s9
	s_add_u32 s2, s18, 0x100000
	global_load_lds_dwordx4 v134, s[18:19]
	s_mov_b32 m0, s27
	s_addc_u32 s3, s19, 0
	s_add_i32 s28, s9, 0x4000
	global_load_lds_dwordx4 v130, s[18:19]
	s_mov_b32 m0, s28
	s_add_i32 s29, s9, 0x6000
	global_load_lds_dwordx4 v134, s[2:3]
	s_mov_b32 m0, s29
	v_mov_b32_e32 v129, v133
	global_load_lds_dwordx4 v130, s[2:3]
	v_mov_b32_e32 v135, v133
	v_mov_b32_e32 v131, v133
	s_cmp_eq_u32 s6, 1
	s_mov_b32 s30, 0
	v_lshl_add_u64 v[6:7], s[20:21], 0, v[132:133]
	v_lshl_add_u64 v[4:5], s[20:21], 0, v[128:129]
	v_lshl_add_u64 v[0:1], s[18:19], 0, v[134:135]
	s_cselect_b64 s[2:3], -1, 0
	s_cmp_lg_u32 s6, 1
	v_lshl_add_u64 v[2:3], s[18:19], 0, v[130:131]
	s_cbranch_scc1 .LBB0_244
	s_barrier
